# grid barrier: acquire-side cache invalidate issued at barrier entry (overlaps the arrival atomics) instead of after the release is observed
# speedup vs baseline: 1.0082x; 1.0082x over previous
.LBB0_797:
	v_readlane_b32 s0, v244, 33
	s_cmp_lg_u32 s0, 0
	s_nop 0
	s_waitcnt vmcnt(0)
	s_waitcnt vmcnt(0) lgkmcnt(0)
	s_barrier
	s_mov_b64 s[0:1], exec
	v_readlane_b32 s2, v246, 4
	v_readlane_b32 s3, v246, 5
	s_and_b64 s[2:3], s[0:1], s[2:3]
	s_mov_b64 exec, s[2:3]
	s_cbranch_execz .LBB0_851
	s_getreg_b32 s2, hwreg(HW_REG_XCC_ID, 0, 4)
	s_waitcnt vmcnt(0) expcnt(0) lgkmcnt(0)
	buffer_inv sc1
	ds_read_b32 v2, v28 offset:4832
	ds_read_b32 v0, v28 offset:4836
	s_and_b32 s7, s2, 15
	s_waitcnt lgkmcnt(1)
	v_cmp_ne_u32_e32 vcc, 0, v2
	s_cbranch_vccnz .LBB0_815
	s_mov_b32 s10, 1
	s_branch .LBB0_802

.LBB0_830:
	s_or_b64 exec, exec, s[8:9]
	s_waitcnt vmcnt(0)
	s_waitcnt vmcnt(0)

.LBB0_848:
	s_or_b64 exec, exec, s[4:5]
	s_mov_b64 s[4:5], exec
	v_mbcnt_lo_u32_b32 v0, s4, 0
	v_mbcnt_hi_u32_b32 v0, s5, v0
	v_cmp_eq_u32_e32 vcc, 0, v0
	s_waitcnt vmcnt(0)
	s_and_saveexec_b64 s[8:9], vcc
	s_cbranch_execz .LBB0_850
	s_bcnt1_i32_b64 s4, s[4:5]
	v_mov_b32_e32 v0, s4
	global_atomic_add v200, v0, s[2:3] offset:1024
